# v115 plus GEMM K-loops: the s_setprio 0 / s_setprio 1 pair in the middle of each 32-MFMA block removed (one uninterrupted high-priority block per phase)
# speedup vs baseline: 1.0042x; 1.0001x over previous
.LBB0_289:
	ds_read_b128 v[148:151], v165
	ds_read_b128 v[152:155], v165 offset:1024
	ds_read_b128 v[156:159], v165 offset:2048
	ds_read_b128 v[168:171], v165 offset:3072
	ds_read_b128 v[172:175], v166
	ds_read_b128 v[176:179], v166 offset:1024
	ds_read_b128 v[180:183], v166 offset:2048
	ds_read_b128 v[184:187], v166 offset:3072
	s_add_u32 s54, s52, 0xfffc0080
	s_addc_u32 s55, s53, -1
	s_cmp_eq_u32 s85, 12
	s_cselect_b32 s57, s29, s55
	s_cselect_b32 s56, s81, s54
	s_cselect_b32 s55, s27, s84
	s_cselect_b32 s54, s82, s83
	v_lshl_add_u64 v[160:161], s[52:53], 0, v[140:141]
	s_add_i32 m0, s51, 0xc000
	ds_read_b128 v[188:191], v167
	ds_read_b128 v[192:195], v167 offset:1024
	ds_read_b128 v[200:203], v167 offset:2048
	ds_read_b128 v[204:207], v167 offset:3072
	ds_read_b128 v[208:211], v167 offset:4096
	ds_read_b128 v[212:215], v167 offset:5120
	ds_read_b128 v[216:219], v167 offset:6144
	ds_read_b128 v[220:223], v167 offset:7168
	global_load_lds_dwordx4 v[160:161], off
	v_lshl_add_u64 v[160:161], s[52:53], 0, v[142:143]
	s_add_i32 m0, s51, 0xe000
	s_nop 0
	global_load_lds_dwordx4 v[160:161], off
	s_waitcnt vmcnt(8)
	s_waitcnt lgkmcnt(0)
	s_barrier
	s_setprio 1
	s_waitcnt lgkmcnt(0)
	v_mfma_f32_16x16x32_bf16 v[126:129], v[148:151], v[188:191], v[126:129]
	v_mfma_f32_16x16x32_bf16 v[122:125], v[156:159], v[188:191], v[122:125]
	v_mfma_f32_16x16x32_bf16 v[110:113], v[148:151], v[200:203], v[110:113]
	v_mfma_f32_16x16x32_bf16 v[106:109], v[156:159], v[200:203], v[106:109]
	v_mfma_f32_16x16x32_bf16 v[94:97], v[148:151], v[208:211], v[94:97]
	v_mfma_f32_16x16x32_bf16 v[90:93], v[156:159], v[208:211], v[90:93]
	v_mfma_f32_16x16x32_bf16 v[78:81], v[148:151], v[216:219], v[78:81]
	v_mfma_f32_16x16x32_bf16 v[74:77], v[156:159], v[216:219], v[74:77]
	v_mfma_f32_16x16x32_bf16 v[126:129], v[152:155], v[192:195], v[126:129]
	v_mfma_f32_16x16x32_bf16 v[122:125], v[168:171], v[192:195], v[122:125]
	v_mfma_f32_16x16x32_bf16 v[110:113], v[152:155], v[204:207], v[110:113]
	v_mfma_f32_16x16x32_bf16 v[106:109], v[168:171], v[204:207], v[106:109]
	v_mfma_f32_16x16x32_bf16 v[94:97], v[152:155], v[212:215], v[94:97]
	v_mfma_f32_16x16x32_bf16 v[90:93], v[168:171], v[212:215], v[90:93]
	v_mfma_f32_16x16x32_bf16 v[78:81], v[152:155], v[220:223], v[78:81]
	v_mfma_f32_16x16x32_bf16 v[74:77], v[168:171], v[220:223], v[74:77]
	v_mfma_f32_16x16x32_bf16 v[118:121], v[172:175], v[188:191], v[118:121]
	v_mfma_f32_16x16x32_bf16 v[114:117], v[180:183], v[188:191], v[114:117]
	v_mfma_f32_16x16x32_bf16 v[102:105], v[172:175], v[200:203], v[102:105]
	v_mfma_f32_16x16x32_bf16 v[98:101], v[180:183], v[200:203], v[98:101]
	v_mfma_f32_16x16x32_bf16 v[86:89], v[172:175], v[208:211], v[86:89]
	v_mfma_f32_16x16x32_bf16 v[82:85], v[180:183], v[208:211], v[82:85]
	v_mfma_f32_16x16x32_bf16 v[70:73], v[172:175], v[216:219], v[70:73]
	v_mfma_f32_16x16x32_bf16 v[66:69], v[180:183], v[216:219], v[66:69]
	v_mfma_f32_16x16x32_bf16 v[118:121], v[176:179], v[192:195], v[118:121]
	v_mfma_f32_16x16x32_bf16 v[114:117], v[184:187], v[192:195], v[114:117]
	v_mfma_f32_16x16x32_bf16 v[102:105], v[176:179], v[204:207], v[102:105]
	v_mfma_f32_16x16x32_bf16 v[98:101], v[184:187], v[204:207], v[98:101]
	v_mfma_f32_16x16x32_bf16 v[86:89], v[176:179], v[212:215], v[86:89]
	v_mfma_f32_16x16x32_bf16 v[82:85], v[184:187], v[212:215], v[82:85]
	v_mfma_f32_16x16x32_bf16 v[70:73], v[176:179], v[220:223], v[70:73]
	v_mfma_f32_16x16x32_bf16 v[66:69], v[184:187], v[220:223], v[66:69]
	s_setprio 0
	s_barrier
	s_add_i32 s86, s74, s64
	v_lshl_add_u64 v[160:161], s[54:55], 0, v[132:133]
	s_mov_b32 m0, s86
	ds_read_b128 v[188:191], v167 offset:16384
	ds_read_b128 v[192:195], v167 offset:17408
	ds_read_b128 v[200:203], v167 offset:18432
	ds_read_b128 v[204:207], v167 offset:19456
	ds_read_b128 v[208:211], v167 offset:20480
	ds_read_b128 v[212:215], v167 offset:21504
	ds_read_b128 v[216:219], v167 offset:22528
	ds_read_b128 v[220:223], v167 offset:23552
	global_load_lds_dwordx4 v[160:161], off
	s_add_i32 m0, s86, 0x2000
	s_add_u32 s86, s54, 0x40000
	v_lshl_add_u64 v[196:197], s[54:55], 0, v[136:137]
	s_addc_u32 s87, s55, 0
	s_add_i32 s88, s75, s64
	global_load_lds_dwordx4 v[196:197], off
	v_lshl_add_u64 v[224:225], s[86:87], 0, v[132:133]
	s_mov_b32 m0, s88
	v_lshl_add_u64 v[226:227], s[56:57], 0, v[134:135]
	global_load_lds_dwordx4 v[224:225], off
	v_lshl_add_u64 v[224:225], s[86:87], 0, v[136:137]
	s_add_i32 m0, s88, 0x2000
	s_nop 0
	global_load_lds_dwordx4 v[224:225], off
	v_lshl_add_u64 v[224:225], s[56:57], 0, v[130:131]
	s_mov_b32 m0, s51
	s_nop 0
	global_load_lds_dwordx4 v[224:225], off
	s_mov_b32 m0, s65
	s_nop 0
	global_load_lds_dwordx4 v[226:227], off
	s_waitcnt vmcnt(8)
	s_waitcnt lgkmcnt(0)
	s_barrier
	s_setprio 1
	s_waitcnt lgkmcnt(0)
	v_mfma_f32_16x16x32_bf16 v[62:65], v[148:151], v[188:191], v[62:65]
	v_mfma_f32_16x16x32_bf16 v[58:61], v[156:159], v[188:191], v[58:61]
	v_mfma_f32_16x16x32_bf16 v[46:49], v[148:151], v[200:203], v[46:49]
	v_mfma_f32_16x16x32_bf16 v[42:45], v[156:159], v[200:203], v[42:45]
	v_mfma_f32_16x16x32_bf16 v[30:33], v[148:151], v[208:211], v[30:33]
	v_mfma_f32_16x16x32_bf16 v[26:29], v[156:159], v[208:211], v[26:29]
	v_mfma_f32_16x16x32_bf16 v[14:17], v[148:151], v[216:219], v[14:17]
	v_mfma_f32_16x16x32_bf16 v[10:13], v[156:159], v[216:219], v[10:13]
	v_mfma_f32_16x16x32_bf16 v[62:65], v[152:155], v[192:195], v[62:65]
	v_mfma_f32_16x16x32_bf16 v[58:61], v[168:171], v[192:195], v[58:61]
	v_mfma_f32_16x16x32_bf16 v[46:49], v[152:155], v[204:207], v[46:49]
	v_mfma_f32_16x16x32_bf16 v[42:45], v[168:171], v[204:207], v[42:45]
	v_mfma_f32_16x16x32_bf16 v[30:33], v[152:155], v[212:215], v[30:33]
	v_mfma_f32_16x16x32_bf16 v[26:29], v[168:171], v[212:215], v[26:29]
	v_mfma_f32_16x16x32_bf16 v[14:17], v[152:155], v[220:223], v[14:17]
	v_mfma_f32_16x16x32_bf16 v[10:13], v[168:171], v[220:223], v[10:13]
	v_mfma_f32_16x16x32_bf16 v[54:57], v[172:175], v[188:191], v[54:57]
	v_mfma_f32_16x16x32_bf16 v[50:53], v[180:183], v[188:191], v[50:53]
	v_mfma_f32_16x16x32_bf16 v[38:41], v[172:175], v[200:203], v[38:41]
	v_mfma_f32_16x16x32_bf16 v[34:37], v[180:183], v[200:203], v[34:37]
	v_mfma_f32_16x16x32_bf16 v[22:25], v[172:175], v[208:211], v[22:25]
	v_mfma_f32_16x16x32_bf16 v[18:21], v[180:183], v[208:211], v[18:21]
	v_mfma_f32_16x16x32_bf16 v[6:9], v[172:175], v[216:219], v[6:9]
	v_mfma_f32_16x16x32_bf16 v[2:5], v[180:183], v[216:219], v[2:5]
	v_mfma_f32_16x16x32_bf16 v[54:57], v[176:179], v[192:195], v[54:57]
	v_mfma_f32_16x16x32_bf16 v[50:53], v[184:187], v[192:195], v[50:53]
	v_mfma_f32_16x16x32_bf16 v[38:41], v[176:179], v[204:207], v[38:41]
	v_mfma_f32_16x16x32_bf16 v[34:37], v[184:187], v[204:207], v[34:37]
	v_mfma_f32_16x16x32_bf16 v[22:25], v[176:179], v[212:215], v[22:25]
	v_mfma_f32_16x16x32_bf16 v[18:21], v[184:187], v[212:215], v[18:21]
	v_mfma_f32_16x16x32_bf16 v[6:9], v[176:179], v[220:223], v[6:9]
	v_mfma_f32_16x16x32_bf16 v[2:5], v[184:187], v[220:223], v[2:5]
	s_setprio 0
	s_barrier
	s_add_i32 s86, 0, 0x18000
	v_add_u32_e32 v138, s86, v162
	s_add_i32 s87, 0, 0x1c000
	ds_read_b128 v[148:151], v138
	ds_read_b128 v[152:155], v138 offset:1024
	ds_read_b128 v[156:159], v138 offset:2048
	ds_read_b128 v[168:171], v138 offset:3072
	v_add_u32_e32 v138, s87, v162
	ds_read_b128 v[172:175], v138
	ds_read_b128 v[176:179], v138 offset:1024
	ds_read_b128 v[180:183], v138 offset:2048
	ds_read_b128 v[184:187], v138 offset:3072
	s_add_u32 s56, s56, 0x40000
	s_addc_u32 s57, s57, 0
	s_mov_b32 m0, s66
	v_lshl_add_u64 v[228:229], s[56:57], 0, v[130:131]
	ds_read_b128 v[188:191], v167 offset:32768
	ds_read_b128 v[192:195], v167 offset:33792
	ds_read_b128 v[200:203], v167 offset:34816
	ds_read_b128 v[204:207], v167 offset:35840
	ds_read_b128 v[208:211], v167 offset:36864
	ds_read_b128 v[212:215], v167 offset:37888
	ds_read_b128 v[216:219], v167 offset:38912
	ds_read_b128 v[220:223], v167 offset:39936
	global_load_lds_dwordx4 v[228:229], off
	v_lshl_add_u64 v[228:229], s[56:57], 0, v[134:135]
	s_mov_b32 m0, s67
	s_nop 0
	global_load_lds_dwordx4 v[228:229], off
	s_waitcnt vmcnt(8)
	s_waitcnt lgkmcnt(0)
	s_barrier
	s_setprio 1
	s_waitcnt lgkmcnt(0)
	v_mfma_f32_16x16x32_bf16 v[126:129], v[148:151], v[188:191], v[126:129]
	v_mfma_f32_16x16x32_bf16 v[122:125], v[156:159], v[188:191], v[122:125]
	v_mfma_f32_16x16x32_bf16 v[110:113], v[148:151], v[200:203], v[110:113]
	v_mfma_f32_16x16x32_bf16 v[106:109], v[156:159], v[200:203], v[106:109]
	v_mfma_f32_16x16x32_bf16 v[94:97], v[148:151], v[208:211], v[94:97]
	v_mfma_f32_16x16x32_bf16 v[90:93], v[156:159], v[208:211], v[90:93]
	v_mfma_f32_16x16x32_bf16 v[78:81], v[148:151], v[216:219], v[78:81]
	v_mfma_f32_16x16x32_bf16 v[74:77], v[156:159], v[216:219], v[74:77]
	v_mfma_f32_16x16x32_bf16 v[126:129], v[152:155], v[192:195], v[126:129]
	v_mfma_f32_16x16x32_bf16 v[122:125], v[168:171], v[192:195], v[122:125]
	v_mfma_f32_16x16x32_bf16 v[110:113], v[152:155], v[204:207], v[110:113]
	v_mfma_f32_16x16x32_bf16 v[106:109], v[168:171], v[204:207], v[106:109]
	v_mfma_f32_16x16x32_bf16 v[94:97], v[152:155], v[212:215], v[94:97]
	v_mfma_f32_16x16x32_bf16 v[90:93], v[168:171], v[212:215], v[90:93]
	v_mfma_f32_16x16x32_bf16 v[78:81], v[152:155], v[220:223], v[78:81]
	v_mfma_f32_16x16x32_bf16 v[74:77], v[168:171], v[220:223], v[74:77]
	v_mfma_f32_16x16x32_bf16 v[118:121], v[172:175], v[188:191], v[118:121]
	v_mfma_f32_16x16x32_bf16 v[114:117], v[180:183], v[188:191], v[114:117]
	v_mfma_f32_16x16x32_bf16 v[102:105], v[172:175], v[200:203], v[102:105]
	v_mfma_f32_16x16x32_bf16 v[98:101], v[180:183], v[200:203], v[98:101]
	v_mfma_f32_16x16x32_bf16 v[86:89], v[172:175], v[208:211], v[86:89]
	v_mfma_f32_16x16x32_bf16 v[82:85], v[180:183], v[208:211], v[82:85]
	v_mfma_f32_16x16x32_bf16 v[70:73], v[172:175], v[216:219], v[70:73]
	v_mfma_f32_16x16x32_bf16 v[66:69], v[180:183], v[216:219], v[66:69]
	v_mfma_f32_16x16x32_bf16 v[118:121], v[176:179], v[192:195], v[118:121]
	v_mfma_f32_16x16x32_bf16 v[114:117], v[184:187], v[192:195], v[114:117]
	v_mfma_f32_16x16x32_bf16 v[102:105], v[176:179], v[204:207], v[102:105]
	v_mfma_f32_16x16x32_bf16 v[98:101], v[184:187], v[204:207], v[98:101]
	v_mfma_f32_16x16x32_bf16 v[86:89], v[176:179], v[212:215], v[86:89]
	v_mfma_f32_16x16x32_bf16 v[82:85], v[184:187], v[212:215], v[82:85]
	v_mfma_f32_16x16x32_bf16 v[70:73], v[176:179], v[220:223], v[70:73]
	v_mfma_f32_16x16x32_bf16 v[66:69], v[184:187], v[220:223], v[66:69]
	s_setprio 0
	s_barrier
	s_add_i32 s56, s86, s64
	v_lshl_add_u64 v[160:161], v[160:161], 0, s[14:15]
	s_mov_b32 m0, s56
	ds_read_b128 v[188:191], v167 offset:49152
	ds_read_b128 v[192:195], v167 offset:50176
	ds_read_b128 v[200:203], v167 offset:51200
	ds_read_b128 v[204:207], v167 offset:52224
	ds_read_b128 v[208:211], v167 offset:53248
	ds_read_b128 v[212:215], v167 offset:54272
	ds_read_b128 v[216:219], v167 offset:55296
	ds_read_b128 v[220:223], v167 offset:56320
	global_load_lds_dwordx4 v[160:161], off
	s_add_i32 m0, s56, 0x2000
	s_add_u32 s54, s54, 0x40080
	v_lshl_add_u64 v[160:161], v[196:197], 0, s[14:15]
	s_addc_u32 s55, s55, 0
	s_add_i32 s56, s87, s64
	global_load_lds_dwordx4 v[160:161], off
	v_lshl_add_u64 v[160:161], s[54:55], 0, v[132:133]
	s_mov_b32 m0, s56
	s_nop 0
	global_load_lds_dwordx4 v[160:161], off
	v_lshl_add_u64 v[160:161], s[54:55], 0, v[136:137]
	s_add_i32 m0, s56, 0x2000
	s_nop 0
	global_load_lds_dwordx4 v[160:161], off
	v_lshl_add_u64 v[160:161], v[224:225], 0, s[14:15]
	s_mov_b32 m0, s68
	s_nop 0
	global_load_lds_dwordx4 v[160:161], off
	v_lshl_add_u64 v[160:161], v[226:227], 0, s[14:15]
	s_mov_b32 m0, s69
	s_nop 0
	global_load_lds_dwordx4 v[160:161], off
	s_waitcnt vmcnt(8)
	s_waitcnt lgkmcnt(0)
	s_barrier
	s_setprio 1
	s_waitcnt lgkmcnt(0)
	v_mfma_f32_16x16x32_bf16 v[62:65], v[148:151], v[188:191], v[62:65]
	v_mfma_f32_16x16x32_bf16 v[58:61], v[156:159], v[188:191], v[58:61]
	v_mfma_f32_16x16x32_bf16 v[46:49], v[148:151], v[200:203], v[46:49]
	v_mfma_f32_16x16x32_bf16 v[42:45], v[156:159], v[200:203], v[42:45]
	v_mfma_f32_16x16x32_bf16 v[30:33], v[148:151], v[208:211], v[30:33]
	v_mfma_f32_16x16x32_bf16 v[26:29], v[156:159], v[208:211], v[26:29]
	v_mfma_f32_16x16x32_bf16 v[14:17], v[148:151], v[216:219], v[14:17]
	v_mfma_f32_16x16x32_bf16 v[10:13], v[156:159], v[216:219], v[10:13]
	v_mfma_f32_16x16x32_bf16 v[62:65], v[152:155], v[192:195], v[62:65]
	v_mfma_f32_16x16x32_bf16 v[58:61], v[168:171], v[192:195], v[58:61]
	v_mfma_f32_16x16x32_bf16 v[46:49], v[152:155], v[204:207], v[46:49]
	v_mfma_f32_16x16x32_bf16 v[42:45], v[168:171], v[204:207], v[42:45]
	v_mfma_f32_16x16x32_bf16 v[30:33], v[152:155], v[212:215], v[30:33]
	v_mfma_f32_16x16x32_bf16 v[26:29], v[168:171], v[212:215], v[26:29]
	v_mfma_f32_16x16x32_bf16 v[14:17], v[152:155], v[220:223], v[14:17]
	v_mfma_f32_16x16x32_bf16 v[10:13], v[168:171], v[220:223], v[10:13]
	v_mfma_f32_16x16x32_bf16 v[54:57], v[172:175], v[188:191], v[54:57]
	v_mfma_f32_16x16x32_bf16 v[50:53], v[180:183], v[188:191], v[50:53]
	v_mfma_f32_16x16x32_bf16 v[38:41], v[172:175], v[200:203], v[38:41]
	v_mfma_f32_16x16x32_bf16 v[34:37], v[180:183], v[200:203], v[34:37]
	v_mfma_f32_16x16x32_bf16 v[22:25], v[172:175], v[208:211], v[22:25]
	v_mfma_f32_16x16x32_bf16 v[18:21], v[180:183], v[208:211], v[18:21]
	v_mfma_f32_16x16x32_bf16 v[6:9], v[172:175], v[216:219], v[6:9]
	v_mfma_f32_16x16x32_bf16 v[2:5], v[180:183], v[216:219], v[2:5]
	v_mfma_f32_16x16x32_bf16 v[54:57], v[176:179], v[192:195], v[54:57]
	v_mfma_f32_16x16x32_bf16 v[50:53], v[184:187], v[192:195], v[50:53]
	v_mfma_f32_16x16x32_bf16 v[38:41], v[176:179], v[204:207], v[38:41]
	v_mfma_f32_16x16x32_bf16 v[34:37], v[184:187], v[204:207], v[34:37]
	v_mfma_f32_16x16x32_bf16 v[22:25], v[176:179], v[212:215], v[22:25]
	v_mfma_f32_16x16x32_bf16 v[18:21], v[184:187], v[212:215], v[18:21]
	v_mfma_f32_16x16x32_bf16 v[6:9], v[176:179], v[220:223], v[6:9]
	v_mfma_f32_16x16x32_bf16 v[2:5], v[184:187], v[220:223], v[2:5]
	s_setprio 0
	s_barrier
	s_add_i32 s85, s85, 2
	s_add_u32 s52, s52, 0x100
	s_addc_u32 s53, s53, 0
	s_add_u32 s83, s83, 0x100
	s_addc_u32 s84, s84, 0
	s_cmp_gt_u32 s85, 13
	s_cbranch_scc0 .LBB0_289
	s_and_b64 vcc, exec, s[18:19]
	s_cbranch_vccz .LBB0_292
	s_barrier

.LBB0_557:
	ds_read_b128 v[130:133], v190
	ds_read_b128 v[134:137], v190 offset:1024
	ds_read_b128 v[138:141], v190 offset:2048
	ds_read_b128 v[142:145], v190 offset:3072
	ds_read_b128 v[146:149], v191
	ds_read_b128 v[150:153], v191 offset:1024
	ds_read_b128 v[170:173], v191 offset:2048
	ds_read_b128 v[174:177], v191 offset:3072
	s_add_u32 s54, s52, 0xfffc0080
	s_addc_u32 s55, s53, -1
	s_cmp_eq_u32 s78, 12
	s_cselect_b32 s57, s47, s55
	s_cselect_b32 s56, s74, s54
	s_cselect_b32 s55, s29, s77
	s_cselect_b32 s54, s75, s76
	v_lshl_add_u64 v[186:187], s[52:53], 0, v[162:163]
	s_add_i32 m0, s11, 0xc000
	ds_read_b128 v[178:181], v192
	ds_read_b128 v[182:185], v192 offset:1024
	ds_read_b128 v[194:197], v192 offset:2048
	ds_read_b128 v[200:203], v192 offset:3072
	ds_read_b128 v[204:207], v192 offset:4096
	ds_read_b128 v[208:211], v192 offset:5120
	ds_read_b128 v[212:215], v192 offset:6144
	ds_read_b128 v[216:219], v192 offset:7168
	global_load_lds_dwordx4 v[186:187], off
	v_lshl_add_u64 v[186:187], s[52:53], 0, v[164:165]
	s_add_i32 m0, s11, 0xe000
	s_nop 0
	global_load_lds_dwordx4 v[186:187], off
	s_waitcnt vmcnt(8)
	s_waitcnt lgkmcnt(0)
	s_barrier
	s_setprio 1
	s_waitcnt lgkmcnt(0)
	v_mfma_f32_16x16x32_bf16 v[126:129], v[130:133], v[178:181], v[126:129]
	v_mfma_f32_16x16x32_bf16 v[122:125], v[138:141], v[178:181], v[122:125]
	v_mfma_f32_16x16x32_bf16 v[110:113], v[130:133], v[194:197], v[110:113]
	v_mfma_f32_16x16x32_bf16 v[106:109], v[138:141], v[194:197], v[106:109]
	v_mfma_f32_16x16x32_bf16 v[94:97], v[130:133], v[204:207], v[94:97]
	v_mfma_f32_16x16x32_bf16 v[90:93], v[138:141], v[204:207], v[90:93]
	v_mfma_f32_16x16x32_bf16 v[78:81], v[130:133], v[212:215], v[78:81]
	v_mfma_f32_16x16x32_bf16 v[74:77], v[138:141], v[212:215], v[74:77]
	v_mfma_f32_16x16x32_bf16 v[126:129], v[134:137], v[182:185], v[126:129]
	v_mfma_f32_16x16x32_bf16 v[122:125], v[142:145], v[182:185], v[122:125]
	v_mfma_f32_16x16x32_bf16 v[110:113], v[134:137], v[200:203], v[110:113]
	v_mfma_f32_16x16x32_bf16 v[106:109], v[142:145], v[200:203], v[106:109]
	v_mfma_f32_16x16x32_bf16 v[94:97], v[134:137], v[208:211], v[94:97]
	v_mfma_f32_16x16x32_bf16 v[90:93], v[142:145], v[208:211], v[90:93]
	v_mfma_f32_16x16x32_bf16 v[78:81], v[134:137], v[216:219], v[78:81]
	v_mfma_f32_16x16x32_bf16 v[74:77], v[142:145], v[216:219], v[74:77]
	v_mfma_f32_16x16x32_bf16 v[118:121], v[146:149], v[178:181], v[118:121]
	v_mfma_f32_16x16x32_bf16 v[114:117], v[170:173], v[178:181], v[114:117]
	v_mfma_f32_16x16x32_bf16 v[102:105], v[146:149], v[194:197], v[102:105]
	v_mfma_f32_16x16x32_bf16 v[98:101], v[170:173], v[194:197], v[98:101]
	v_mfma_f32_16x16x32_bf16 v[86:89], v[146:149], v[204:207], v[86:89]
	v_mfma_f32_16x16x32_bf16 v[82:85], v[170:173], v[204:207], v[82:85]
	v_mfma_f32_16x16x32_bf16 v[70:73], v[146:149], v[212:215], v[70:73]
	v_mfma_f32_16x16x32_bf16 v[66:69], v[170:173], v[212:215], v[66:69]
	v_mfma_f32_16x16x32_bf16 v[118:121], v[150:153], v[182:185], v[118:121]
	v_mfma_f32_16x16x32_bf16 v[114:117], v[174:177], v[182:185], v[114:117]
	v_mfma_f32_16x16x32_bf16 v[102:105], v[150:153], v[200:203], v[102:105]
	v_mfma_f32_16x16x32_bf16 v[98:101], v[174:177], v[200:203], v[98:101]
	v_mfma_f32_16x16x32_bf16 v[86:89], v[150:153], v[208:211], v[86:89]
	v_mfma_f32_16x16x32_bf16 v[82:85], v[174:177], v[208:211], v[82:85]
	v_mfma_f32_16x16x32_bf16 v[70:73], v[150:153], v[216:219], v[70:73]
	v_mfma_f32_16x16x32_bf16 v[66:69], v[174:177], v[216:219], v[66:69]
	s_setprio 0
	s_barrier
	s_add_i32 s79, s71, s62
	v_lshl_add_u64 v[186:187], s[54:55], 0, v[156:157]
	s_mov_b32 m0, s79
	ds_read_b128 v[178:181], v192 offset:16384
	ds_read_b128 v[182:185], v192 offset:17408
	ds_read_b128 v[194:197], v192 offset:18432
	ds_read_b128 v[200:203], v192 offset:19456
	ds_read_b128 v[204:207], v192 offset:20480
	ds_read_b128 v[208:211], v192 offset:21504
	ds_read_b128 v[212:215], v192 offset:22528
	ds_read_b128 v[216:219], v192 offset:23552
	global_load_lds_dwordx4 v[186:187], off
	s_add_i32 m0, s79, 0x2000
	s_add_u32 s80, s54, 0x40000
	v_lshl_add_u64 v[220:221], s[54:55], 0, v[160:161]
	s_addc_u32 s81, s55, 0
	s_add_i32 s79, s72, s62
	global_load_lds_dwordx4 v[220:221], off
	v_lshl_add_u64 v[222:223], s[80:81], 0, v[156:157]
	s_mov_b32 m0, s79
	v_lshl_add_u64 v[224:225], s[56:57], 0, v[158:159]
	global_load_lds_dwordx4 v[222:223], off
	v_lshl_add_u64 v[222:223], s[80:81], 0, v[160:161]
	s_add_i32 m0, s79, 0x2000
	s_nop 0
	global_load_lds_dwordx4 v[222:223], off
	v_lshl_add_u64 v[222:223], s[56:57], 0, v[154:155]
	s_mov_b32 m0, s11
	s_nop 0
	global_load_lds_dwordx4 v[222:223], off
	s_mov_b32 m0, s63
	s_nop 0
	global_load_lds_dwordx4 v[224:225], off
	s_waitcnt vmcnt(8)
	s_waitcnt lgkmcnt(0)
	s_barrier
	s_setprio 1
	s_waitcnt lgkmcnt(0)
	v_mfma_f32_16x16x32_bf16 v[62:65], v[130:133], v[178:181], v[62:65]
	v_mfma_f32_16x16x32_bf16 v[58:61], v[138:141], v[178:181], v[58:61]
	v_mfma_f32_16x16x32_bf16 v[46:49], v[130:133], v[194:197], v[46:49]
	v_mfma_f32_16x16x32_bf16 v[42:45], v[138:141], v[194:197], v[42:45]
	v_mfma_f32_16x16x32_bf16 v[30:33], v[130:133], v[204:207], v[30:33]
	v_mfma_f32_16x16x32_bf16 v[26:29], v[138:141], v[204:207], v[26:29]
	v_mfma_f32_16x16x32_bf16 v[14:17], v[130:133], v[212:215], v[14:17]
	v_mfma_f32_16x16x32_bf16 v[10:13], v[138:141], v[212:215], v[10:13]
	v_mfma_f32_16x16x32_bf16 v[62:65], v[134:137], v[182:185], v[62:65]
	v_mfma_f32_16x16x32_bf16 v[58:61], v[142:145], v[182:185], v[58:61]
	v_mfma_f32_16x16x32_bf16 v[46:49], v[134:137], v[200:203], v[46:49]
	v_mfma_f32_16x16x32_bf16 v[42:45], v[142:145], v[200:203], v[42:45]
	v_mfma_f32_16x16x32_bf16 v[30:33], v[134:137], v[208:211], v[30:33]
	v_mfma_f32_16x16x32_bf16 v[26:29], v[142:145], v[208:211], v[26:29]
	v_mfma_f32_16x16x32_bf16 v[14:17], v[134:137], v[216:219], v[14:17]
	v_mfma_f32_16x16x32_bf16 v[10:13], v[142:145], v[216:219], v[10:13]
	v_mfma_f32_16x16x32_bf16 v[54:57], v[146:149], v[178:181], v[54:57]
	v_mfma_f32_16x16x32_bf16 v[50:53], v[170:173], v[178:181], v[50:53]
	v_mfma_f32_16x16x32_bf16 v[38:41], v[146:149], v[194:197], v[38:41]
	v_mfma_f32_16x16x32_bf16 v[34:37], v[170:173], v[194:197], v[34:37]
	v_mfma_f32_16x16x32_bf16 v[22:25], v[146:149], v[204:207], v[22:25]
	v_mfma_f32_16x16x32_bf16 v[18:21], v[170:173], v[204:207], v[18:21]
	v_mfma_f32_16x16x32_bf16 v[6:9], v[146:149], v[212:215], v[6:9]
	v_mfma_f32_16x16x32_bf16 v[2:5], v[170:173], v[212:215], v[2:5]
	v_mfma_f32_16x16x32_bf16 v[54:57], v[150:153], v[182:185], v[54:57]
	v_mfma_f32_16x16x32_bf16 v[50:53], v[174:177], v[182:185], v[50:53]
	v_mfma_f32_16x16x32_bf16 v[38:41], v[150:153], v[200:203], v[38:41]
	v_mfma_f32_16x16x32_bf16 v[34:37], v[174:177], v[200:203], v[34:37]
	v_mfma_f32_16x16x32_bf16 v[22:25], v[150:153], v[208:211], v[22:25]
	v_mfma_f32_16x16x32_bf16 v[18:21], v[174:177], v[208:211], v[18:21]
	v_mfma_f32_16x16x32_bf16 v[6:9], v[150:153], v[216:219], v[6:9]
	v_mfma_f32_16x16x32_bf16 v[2:5], v[174:177], v[216:219], v[2:5]
	s_setprio 0
	s_barrier
	s_add_i32 s79, 0, 0x18000
	s_add_i32 s80, 0, 0x1c000
	v_add_u32_e32 v142, s79, v188
	v_add_u32_e32 v174, s80, v188
	ds_read_b128 v[130:133], v142
	ds_read_b128 v[134:137], v142 offset:1024
	ds_read_b128 v[138:141], v142 offset:2048
	ds_read_b128 v[142:145], v142 offset:3072
	ds_read_b128 v[146:149], v174
	ds_read_b128 v[150:153], v174 offset:1024
	ds_read_b128 v[170:173], v174 offset:2048
	ds_read_b128 v[174:177], v174 offset:3072
	s_add_u32 s56, s56, 0x40000
	s_addc_u32 s57, s57, 0
	s_mov_b32 m0, s64
	v_lshl_add_u64 v[226:227], s[56:57], 0, v[154:155]
	ds_read_b128 v[178:181], v192 offset:32768
	ds_read_b128 v[182:185], v192 offset:33792
	ds_read_b128 v[194:197], v192 offset:34816
	ds_read_b128 v[200:203], v192 offset:35840
	ds_read_b128 v[204:207], v192 offset:36864
	ds_read_b128 v[208:211], v192 offset:37888
	ds_read_b128 v[212:215], v192 offset:38912
	ds_read_b128 v[216:219], v192 offset:39936
	global_load_lds_dwordx4 v[226:227], off
	v_lshl_add_u64 v[226:227], s[56:57], 0, v[158:159]
	s_mov_b32 m0, s65
	s_nop 0
	global_load_lds_dwordx4 v[226:227], off
	s_waitcnt vmcnt(8)
	s_waitcnt lgkmcnt(0)
	s_barrier
	s_setprio 1
	s_waitcnt lgkmcnt(0)
	v_mfma_f32_16x16x32_bf16 v[126:129], v[130:133], v[178:181], v[126:129]
	v_mfma_f32_16x16x32_bf16 v[122:125], v[138:141], v[178:181], v[122:125]
	v_mfma_f32_16x16x32_bf16 v[110:113], v[130:133], v[194:197], v[110:113]
	v_mfma_f32_16x16x32_bf16 v[106:109], v[138:141], v[194:197], v[106:109]
	v_mfma_f32_16x16x32_bf16 v[94:97], v[130:133], v[204:207], v[94:97]
	v_mfma_f32_16x16x32_bf16 v[90:93], v[138:141], v[204:207], v[90:93]
	v_mfma_f32_16x16x32_bf16 v[78:81], v[130:133], v[212:215], v[78:81]
	v_mfma_f32_16x16x32_bf16 v[74:77], v[138:141], v[212:215], v[74:77]
	v_mfma_f32_16x16x32_bf16 v[126:129], v[134:137], v[182:185], v[126:129]
	v_mfma_f32_16x16x32_bf16 v[122:125], v[142:145], v[182:185], v[122:125]
	v_mfma_f32_16x16x32_bf16 v[110:113], v[134:137], v[200:203], v[110:113]
	v_mfma_f32_16x16x32_bf16 v[106:109], v[142:145], v[200:203], v[106:109]
	v_mfma_f32_16x16x32_bf16 v[94:97], v[134:137], v[208:211], v[94:97]
	v_mfma_f32_16x16x32_bf16 v[90:93], v[142:145], v[208:211], v[90:93]
	v_mfma_f32_16x16x32_bf16 v[78:81], v[134:137], v[216:219], v[78:81]
	v_mfma_f32_16x16x32_bf16 v[74:77], v[142:145], v[216:219], v[74:77]
	v_mfma_f32_16x16x32_bf16 v[118:121], v[146:149], v[178:181], v[118:121]
	v_mfma_f32_16x16x32_bf16 v[114:117], v[170:173], v[178:181], v[114:117]
	v_mfma_f32_16x16x32_bf16 v[102:105], v[146:149], v[194:197], v[102:105]
	v_mfma_f32_16x16x32_bf16 v[98:101], v[170:173], v[194:197], v[98:101]
	v_mfma_f32_16x16x32_bf16 v[86:89], v[146:149], v[204:207], v[86:89]
	v_mfma_f32_16x16x32_bf16 v[82:85], v[170:173], v[204:207], v[82:85]
	v_mfma_f32_16x16x32_bf16 v[70:73], v[146:149], v[212:215], v[70:73]
	v_mfma_f32_16x16x32_bf16 v[66:69], v[170:173], v[212:215], v[66:69]
	v_mfma_f32_16x16x32_bf16 v[118:121], v[150:153], v[182:185], v[118:121]
	v_mfma_f32_16x16x32_bf16 v[114:117], v[174:177], v[182:185], v[114:117]
	v_mfma_f32_16x16x32_bf16 v[102:105], v[150:153], v[200:203], v[102:105]
	v_mfma_f32_16x16x32_bf16 v[98:101], v[174:177], v[200:203], v[98:101]
	v_mfma_f32_16x16x32_bf16 v[86:89], v[150:153], v[208:211], v[86:89]
	v_mfma_f32_16x16x32_bf16 v[82:85], v[174:177], v[208:211], v[82:85]
	v_mfma_f32_16x16x32_bf16 v[70:73], v[150:153], v[216:219], v[70:73]
	v_mfma_f32_16x16x32_bf16 v[66:69], v[174:177], v[216:219], v[66:69]
	s_setprio 0
	s_barrier
	s_add_i32 s56, s79, s62
	v_lshl_add_u64 v[186:187], v[186:187], 0, s[18:19]
	s_mov_b32 m0, s56
	ds_read_b128 v[178:181], v192 offset:49152
	ds_read_b128 v[182:185], v192 offset:50176
	ds_read_b128 v[194:197], v192 offset:51200
	ds_read_b128 v[200:203], v192 offset:52224
	ds_read_b128 v[204:207], v192 offset:53248
	ds_read_b128 v[208:211], v192 offset:54272
	ds_read_b128 v[212:215], v192 offset:55296
	ds_read_b128 v[216:219], v192 offset:56320
	global_load_lds_dwordx4 v[186:187], off
	s_add_i32 m0, s56, 0x2000
	s_add_u32 s54, s54, 0x40080
	v_lshl_add_u64 v[186:187], v[220:221], 0, s[18:19]
	s_addc_u32 s55, s55, 0
	s_add_i32 s56, s80, s62
	global_load_lds_dwordx4 v[186:187], off
	v_lshl_add_u64 v[186:187], s[54:55], 0, v[156:157]
	s_mov_b32 m0, s56
	s_nop 0
	global_load_lds_dwordx4 v[186:187], off
	v_lshl_add_u64 v[186:187], s[54:55], 0, v[160:161]
	s_add_i32 m0, s56, 0x2000
	s_nop 0
	global_load_lds_dwordx4 v[186:187], off
	v_lshl_add_u64 v[186:187], v[222:223], 0, s[18:19]
	s_mov_b32 m0, s67
	s_nop 0
	global_load_lds_dwordx4 v[186:187], off
	v_lshl_add_u64 v[186:187], v[224:225], 0, s[18:19]
	s_mov_b32 m0, s68
	s_nop 0
	global_load_lds_dwordx4 v[186:187], off
	s_waitcnt vmcnt(8)
	s_waitcnt lgkmcnt(0)
	s_barrier
	s_setprio 1
	s_waitcnt lgkmcnt(0)
	v_mfma_f32_16x16x32_bf16 v[62:65], v[130:133], v[178:181], v[62:65]
	v_mfma_f32_16x16x32_bf16 v[58:61], v[138:141], v[178:181], v[58:61]
	v_mfma_f32_16x16x32_bf16 v[46:49], v[130:133], v[194:197], v[46:49]
	v_mfma_f32_16x16x32_bf16 v[42:45], v[138:141], v[194:197], v[42:45]
	v_mfma_f32_16x16x32_bf16 v[30:33], v[130:133], v[204:207], v[30:33]
	v_mfma_f32_16x16x32_bf16 v[26:29], v[138:141], v[204:207], v[26:29]
	v_mfma_f32_16x16x32_bf16 v[14:17], v[130:133], v[212:215], v[14:17]
	v_mfma_f32_16x16x32_bf16 v[10:13], v[138:141], v[212:215], v[10:13]
	v_mfma_f32_16x16x32_bf16 v[62:65], v[134:137], v[182:185], v[62:65]
	v_mfma_f32_16x16x32_bf16 v[58:61], v[142:145], v[182:185], v[58:61]
	v_mfma_f32_16x16x32_bf16 v[46:49], v[134:137], v[200:203], v[46:49]
	v_mfma_f32_16x16x32_bf16 v[42:45], v[142:145], v[200:203], v[42:45]
	v_mfma_f32_16x16x32_bf16 v[30:33], v[134:137], v[208:211], v[30:33]
	v_mfma_f32_16x16x32_bf16 v[26:29], v[142:145], v[208:211], v[26:29]
	v_mfma_f32_16x16x32_bf16 v[14:17], v[134:137], v[216:219], v[14:17]
	v_mfma_f32_16x16x32_bf16 v[10:13], v[142:145], v[216:219], v[10:13]
	v_mfma_f32_16x16x32_bf16 v[54:57], v[146:149], v[178:181], v[54:57]
	v_mfma_f32_16x16x32_bf16 v[50:53], v[170:173], v[178:181], v[50:53]
	v_mfma_f32_16x16x32_bf16 v[38:41], v[146:149], v[194:197], v[38:41]
	v_mfma_f32_16x16x32_bf16 v[34:37], v[170:173], v[194:197], v[34:37]
	v_mfma_f32_16x16x32_bf16 v[22:25], v[146:149], v[204:207], v[22:25]
	v_mfma_f32_16x16x32_bf16 v[18:21], v[170:173], v[204:207], v[18:21]
	v_mfma_f32_16x16x32_bf16 v[6:9], v[146:149], v[212:215], v[6:9]
	v_mfma_f32_16x16x32_bf16 v[2:5], v[170:173], v[212:215], v[2:5]
	v_mfma_f32_16x16x32_bf16 v[54:57], v[150:153], v[182:185], v[54:57]
	v_mfma_f32_16x16x32_bf16 v[50:53], v[174:177], v[182:185], v[50:53]
	v_mfma_f32_16x16x32_bf16 v[38:41], v[150:153], v[200:203], v[38:41]
	v_mfma_f32_16x16x32_bf16 v[34:37], v[174:177], v[200:203], v[34:37]
	v_mfma_f32_16x16x32_bf16 v[22:25], v[150:153], v[208:211], v[22:25]
	v_mfma_f32_16x16x32_bf16 v[18:21], v[174:177], v[208:211], v[18:21]
	v_mfma_f32_16x16x32_bf16 v[6:9], v[150:153], v[216:219], v[6:9]
	v_mfma_f32_16x16x32_bf16 v[2:5], v[174:177], v[216:219], v[2:5]
	s_setprio 0
	s_barrier
	s_add_i32 s78, s78, 2
	s_add_u32 s52, s52, 0x100
	s_addc_u32 s53, s53, 0
	s_add_u32 s76, s76, 0x100
	s_addc_u32 s77, s77, 0
	s_cmp_gt_u32 s78, 13
	s_cbranch_scc0 .LBB0_557
	s_and_b64 vcc, exec, s[20:21]
	s_cbranch_vccz .LBB0_560
	s_barrier

.LBB0_713:
	ds_read_b128 v[130:133], v243
	ds_read_b128 v[134:137], v243 offset:1024
	ds_read_b128 v[138:141], v243 offset:2048
	ds_read_b128 v[142:145], v243 offset:3072
	ds_read_b128 v[146:149], v244
	ds_read_b128 v[150:153], v244 offset:1024
	ds_read_b128 v[154:157], v244 offset:2048
	ds_read_b128 v[158:161], v244 offset:3072
	s_add_u32 s62, s12, 0xfffc0080
	s_addc_u32 s63, s13, -1
	s_cmp_eq_u32 s95, 12
	s_cselect_b32 s65, s57, s63
	s_cselect_b32 s64, s67, s62
	s_cselect_b32 s63, s55, s94
	s_cselect_b32 s62, s92, s93
	v_lshl_add_u64 v[194:195], s[12:13], 0, v[216:217]
	s_add_i32 m0, s25, 0xc000
	ds_read_b128 v[162:165], v245
	ds_read_b128 v[166:169], v245 offset:1024
	ds_read_b128 v[170:173], v245 offset:2048
	ds_read_b128 v[174:177], v245 offset:3072
	ds_read_b128 v[178:181], v245 offset:4096
	ds_read_b128 v[182:185], v245 offset:5120
	ds_read_b128 v[186:189], v245 offset:6144
	ds_read_b128 v[190:193], v245 offset:7168
	global_load_lds_dwordx4 v[194:195], off
	v_lshl_add_u64 v[194:195], s[12:13], 0, v[218:219]
	s_add_i32 m0, s25, 0xe000
	s_nop 0
	global_load_lds_dwordx4 v[194:195], off
	s_waitcnt vmcnt(8)
	s_waitcnt lgkmcnt(0)
	s_barrier
	s_setprio 1
	s_waitcnt lgkmcnt(0)
	v_mfma_f32_16x16x32_bf16 v[126:129], v[130:133], v[162:165], v[126:129]
	v_mfma_f32_16x16x32_bf16 v[122:125], v[138:141], v[162:165], v[122:125]
	v_mfma_f32_16x16x32_bf16 v[110:113], v[130:133], v[170:173], v[110:113]
	v_mfma_f32_16x16x32_bf16 v[106:109], v[138:141], v[170:173], v[106:109]
	v_mfma_f32_16x16x32_bf16 v[94:97], v[130:133], v[178:181], v[94:97]
	v_mfma_f32_16x16x32_bf16 v[90:93], v[138:141], v[178:181], v[90:93]
	v_mfma_f32_16x16x32_bf16 v[78:81], v[130:133], v[186:189], v[78:81]
	v_mfma_f32_16x16x32_bf16 v[74:77], v[138:141], v[186:189], v[74:77]
	v_mfma_f32_16x16x32_bf16 v[126:129], v[134:137], v[166:169], v[126:129]
	v_mfma_f32_16x16x32_bf16 v[122:125], v[142:145], v[166:169], v[122:125]
	v_mfma_f32_16x16x32_bf16 v[110:113], v[134:137], v[174:177], v[110:113]
	v_mfma_f32_16x16x32_bf16 v[106:109], v[142:145], v[174:177], v[106:109]
	v_mfma_f32_16x16x32_bf16 v[94:97], v[134:137], v[182:185], v[94:97]
	v_mfma_f32_16x16x32_bf16 v[90:93], v[142:145], v[182:185], v[90:93]
	v_mfma_f32_16x16x32_bf16 v[78:81], v[134:137], v[190:193], v[78:81]
	v_mfma_f32_16x16x32_bf16 v[74:77], v[142:145], v[190:193], v[74:77]
	v_mfma_f32_16x16x32_bf16 v[118:121], v[146:149], v[162:165], v[118:121]
	v_mfma_f32_16x16x32_bf16 v[114:117], v[154:157], v[162:165], v[114:117]
	v_mfma_f32_16x16x32_bf16 v[102:105], v[146:149], v[170:173], v[102:105]
	v_mfma_f32_16x16x32_bf16 v[98:101], v[154:157], v[170:173], v[98:101]
	v_mfma_f32_16x16x32_bf16 v[86:89], v[146:149], v[178:181], v[86:89]
	v_mfma_f32_16x16x32_bf16 v[82:85], v[154:157], v[178:181], v[82:85]
	v_mfma_f32_16x16x32_bf16 v[70:73], v[146:149], v[186:189], v[70:73]
	v_mfma_f32_16x16x32_bf16 v[66:69], v[154:157], v[186:189], v[66:69]
	v_mfma_f32_16x16x32_bf16 v[118:121], v[150:153], v[166:169], v[118:121]
	v_mfma_f32_16x16x32_bf16 v[114:117], v[158:161], v[166:169], v[114:117]
	v_mfma_f32_16x16x32_bf16 v[102:105], v[150:153], v[174:177], v[102:105]
	v_mfma_f32_16x16x32_bf16 v[98:101], v[158:161], v[174:177], v[98:101]
	v_mfma_f32_16x16x32_bf16 v[86:89], v[150:153], v[182:185], v[86:89]
	v_mfma_f32_16x16x32_bf16 v[82:85], v[158:161], v[182:185], v[82:85]
	v_mfma_f32_16x16x32_bf16 v[70:73], v[150:153], v[190:193], v[70:73]
	v_mfma_f32_16x16x32_bf16 v[66:69], v[158:161], v[190:193], v[66:69]
	s_setprio 0
	s_barrier
	s_add_i32 s96, s85, s73
	v_lshl_add_u64 v[194:195], s[62:63], 0, v[202:203]
	s_mov_b32 m0, s96
	ds_read_b128 v[162:165], v245 offset:16384
	ds_read_b128 v[166:169], v245 offset:17408
	ds_read_b128 v[170:173], v245 offset:18432
	ds_read_b128 v[174:177], v245 offset:19456
	ds_read_b128 v[178:181], v245 offset:20480
	ds_read_b128 v[182:185], v245 offset:21504
	ds_read_b128 v[186:189], v245 offset:22528
	ds_read_b128 v[190:193], v245 offset:23552
	global_load_lds_dwordx4 v[194:195], off
	s_add_i32 m0, s96, 0x2000
	s_add_u32 s96, s62, 0x40000
	v_lshl_add_u64 v[196:197], s[62:63], 0, v[206:207]
	s_addc_u32 s97, s63, 0
	s_add_i32 vcc_lo, s86, s73
	global_load_lds_dwordx4 v[196:197], off
	v_lshl_add_u64 v[220:221], s[96:97], 0, v[202:203]
	s_mov_b32 m0, vcc_lo
	v_lshl_add_u64 v[222:223], s[64:65], 0, v[204:205]
	global_load_lds_dwordx4 v[220:221], off
	v_lshl_add_u64 v[220:221], s[96:97], 0, v[206:207]
	s_add_i32 m0, vcc_lo, 0x2000
	s_nop 0
	global_load_lds_dwordx4 v[220:221], off
	v_lshl_add_u64 v[220:221], s[64:65], 0, v[200:201]
	s_mov_b32 m0, s25
	s_nop 0
	global_load_lds_dwordx4 v[220:221], off
	s_mov_b32 m0, s74
	s_nop 0
	global_load_lds_dwordx4 v[222:223], off
	s_waitcnt vmcnt(8)
	s_waitcnt lgkmcnt(0)
	s_barrier
	s_setprio 1
	s_waitcnt lgkmcnt(0)
	v_mfma_f32_16x16x32_bf16 v[62:65], v[130:133], v[162:165], v[62:65]
	v_mfma_f32_16x16x32_bf16 v[58:61], v[138:141], v[162:165], v[58:61]
	v_mfma_f32_16x16x32_bf16 v[46:49], v[130:133], v[170:173], v[46:49]
	v_mfma_f32_16x16x32_bf16 v[42:45], v[138:141], v[170:173], v[42:45]
	v_mfma_f32_16x16x32_bf16 v[30:33], v[130:133], v[178:181], v[30:33]
	v_mfma_f32_16x16x32_bf16 v[26:29], v[138:141], v[178:181], v[26:29]
	v_mfma_f32_16x16x32_bf16 v[14:17], v[130:133], v[186:189], v[14:17]
	v_mfma_f32_16x16x32_bf16 v[10:13], v[138:141], v[186:189], v[10:13]
	v_mfma_f32_16x16x32_bf16 v[62:65], v[134:137], v[166:169], v[62:65]
	v_mfma_f32_16x16x32_bf16 v[58:61], v[142:145], v[166:169], v[58:61]
	v_mfma_f32_16x16x32_bf16 v[46:49], v[134:137], v[174:177], v[46:49]
	v_mfma_f32_16x16x32_bf16 v[42:45], v[142:145], v[174:177], v[42:45]
	v_mfma_f32_16x16x32_bf16 v[30:33], v[134:137], v[182:185], v[30:33]
	v_mfma_f32_16x16x32_bf16 v[26:29], v[142:145], v[182:185], v[26:29]
	v_mfma_f32_16x16x32_bf16 v[14:17], v[134:137], v[190:193], v[14:17]
	v_mfma_f32_16x16x32_bf16 v[10:13], v[142:145], v[190:193], v[10:13]
	v_mfma_f32_16x16x32_bf16 v[54:57], v[146:149], v[162:165], v[54:57]
	v_mfma_f32_16x16x32_bf16 v[50:53], v[154:157], v[162:165], v[50:53]
	v_mfma_f32_16x16x32_bf16 v[38:41], v[146:149], v[170:173], v[38:41]
	v_mfma_f32_16x16x32_bf16 v[34:37], v[154:157], v[170:173], v[34:37]
	v_mfma_f32_16x16x32_bf16 v[22:25], v[146:149], v[178:181], v[22:25]
	v_mfma_f32_16x16x32_bf16 v[18:21], v[154:157], v[178:181], v[18:21]
	v_mfma_f32_16x16x32_bf16 v[6:9], v[146:149], v[186:189], v[6:9]
	v_mfma_f32_16x16x32_bf16 v[2:5], v[154:157], v[186:189], v[2:5]
	v_mfma_f32_16x16x32_bf16 v[54:57], v[150:153], v[166:169], v[54:57]
	v_mfma_f32_16x16x32_bf16 v[50:53], v[158:161], v[166:169], v[50:53]
	v_mfma_f32_16x16x32_bf16 v[38:41], v[150:153], v[174:177], v[38:41]
	v_mfma_f32_16x16x32_bf16 v[34:37], v[158:161], v[174:177], v[34:37]
	v_mfma_f32_16x16x32_bf16 v[22:25], v[150:153], v[182:185], v[22:25]
	v_mfma_f32_16x16x32_bf16 v[18:21], v[158:161], v[182:185], v[18:21]
	v_mfma_f32_16x16x32_bf16 v[6:9], v[150:153], v[190:193], v[6:9]
	v_mfma_f32_16x16x32_bf16 v[2:5], v[158:161], v[190:193], v[2:5]
	s_setprio 0
	s_barrier
	s_add_i32 s96, 0, 0x18000
	s_add_i32 s97, 0, 0x1c000
	v_add_u32_e32 v142, s96, v199
	v_add_u32_e32 v158, s97, v199
	ds_read_b128 v[130:133], v142
	ds_read_b128 v[134:137], v142 offset:1024
	ds_read_b128 v[138:141], v142 offset:2048
	ds_read_b128 v[142:145], v142 offset:3072
	ds_read_b128 v[146:149], v158
	ds_read_b128 v[150:153], v158 offset:1024
	ds_read_b128 v[154:157], v158 offset:2048
	ds_read_b128 v[158:161], v158 offset:3072
	s_add_u32 s64, s64, 0x40000
	s_addc_u32 s65, s65, 0
	s_mov_b32 m0, s75
	v_lshl_add_u64 v[224:225], s[64:65], 0, v[200:201]
	ds_read_b128 v[162:165], v245 offset:32768
	ds_read_b128 v[166:169], v245 offset:33792
	ds_read_b128 v[170:173], v245 offset:34816
	ds_read_b128 v[174:177], v245 offset:35840
	ds_read_b128 v[178:181], v245 offset:36864
	ds_read_b128 v[182:185], v245 offset:37888
	ds_read_b128 v[186:189], v245 offset:38912
	ds_read_b128 v[190:193], v245 offset:39936
	global_load_lds_dwordx4 v[224:225], off
	v_lshl_add_u64 v[224:225], s[64:65], 0, v[204:205]
	s_mov_b32 m0, s76
	s_nop 0
	global_load_lds_dwordx4 v[224:225], off
	s_waitcnt vmcnt(8)
	s_waitcnt lgkmcnt(0)
	s_barrier
	s_setprio 1
	s_waitcnt lgkmcnt(0)
	v_mfma_f32_16x16x32_bf16 v[126:129], v[130:133], v[162:165], v[126:129]
	v_mfma_f32_16x16x32_bf16 v[122:125], v[138:141], v[162:165], v[122:125]
	v_mfma_f32_16x16x32_bf16 v[110:113], v[130:133], v[170:173], v[110:113]
	v_mfma_f32_16x16x32_bf16 v[106:109], v[138:141], v[170:173], v[106:109]
	v_mfma_f32_16x16x32_bf16 v[94:97], v[130:133], v[178:181], v[94:97]
	v_mfma_f32_16x16x32_bf16 v[90:93], v[138:141], v[178:181], v[90:93]
	v_mfma_f32_16x16x32_bf16 v[78:81], v[130:133], v[186:189], v[78:81]
	v_mfma_f32_16x16x32_bf16 v[74:77], v[138:141], v[186:189], v[74:77]
	v_mfma_f32_16x16x32_bf16 v[126:129], v[134:137], v[166:169], v[126:129]
	v_mfma_f32_16x16x32_bf16 v[122:125], v[142:145], v[166:169], v[122:125]
	v_mfma_f32_16x16x32_bf16 v[110:113], v[134:137], v[174:177], v[110:113]
	v_mfma_f32_16x16x32_bf16 v[106:109], v[142:145], v[174:177], v[106:109]
	v_mfma_f32_16x16x32_bf16 v[94:97], v[134:137], v[182:185], v[94:97]
	v_mfma_f32_16x16x32_bf16 v[90:93], v[142:145], v[182:185], v[90:93]
	v_mfma_f32_16x16x32_bf16 v[78:81], v[134:137], v[190:193], v[78:81]
	v_mfma_f32_16x16x32_bf16 v[74:77], v[142:145], v[190:193], v[74:77]
	v_mfma_f32_16x16x32_bf16 v[118:121], v[146:149], v[162:165], v[118:121]
	v_mfma_f32_16x16x32_bf16 v[114:117], v[154:157], v[162:165], v[114:117]
	v_mfma_f32_16x16x32_bf16 v[102:105], v[146:149], v[170:173], v[102:105]
	v_mfma_f32_16x16x32_bf16 v[98:101], v[154:157], v[170:173], v[98:101]
	v_mfma_f32_16x16x32_bf16 v[86:89], v[146:149], v[178:181], v[86:89]
	v_mfma_f32_16x16x32_bf16 v[82:85], v[154:157], v[178:181], v[82:85]
	v_mfma_f32_16x16x32_bf16 v[70:73], v[146:149], v[186:189], v[70:73]
	v_mfma_f32_16x16x32_bf16 v[66:69], v[154:157], v[186:189], v[66:69]
	v_mfma_f32_16x16x32_bf16 v[118:121], v[150:153], v[166:169], v[118:121]
	v_mfma_f32_16x16x32_bf16 v[114:117], v[158:161], v[166:169], v[114:117]
	v_mfma_f32_16x16x32_bf16 v[102:105], v[150:153], v[174:177], v[102:105]
	v_mfma_f32_16x16x32_bf16 v[98:101], v[158:161], v[174:177], v[98:101]
	v_mfma_f32_16x16x32_bf16 v[86:89], v[150:153], v[182:185], v[86:89]
	v_mfma_f32_16x16x32_bf16 v[82:85], v[158:161], v[182:185], v[82:85]
	v_mfma_f32_16x16x32_bf16 v[70:73], v[150:153], v[190:193], v[70:73]
	v_mfma_f32_16x16x32_bf16 v[66:69], v[158:161], v[190:193], v[66:69]
	s_setprio 0
	s_barrier
	s_add_i32 s64, s96, s73
	v_lshl_add_u64 v[194:195], v[194:195], 0, s[26:27]
	s_mov_b32 m0, s64
	ds_read_b128 v[162:165], v245 offset:49152
	ds_read_b128 v[166:169], v245 offset:50176
	ds_read_b128 v[170:173], v245 offset:51200
	ds_read_b128 v[174:177], v245 offset:52224
	ds_read_b128 v[178:181], v245 offset:53248
	ds_read_b128 v[182:185], v245 offset:54272
	ds_read_b128 v[186:189], v245 offset:55296
	ds_read_b128 v[190:193], v245 offset:56320
	global_load_lds_dwordx4 v[194:195], off
	s_add_i32 m0, s64, 0x2000
	s_add_u32 s62, s62, 0x40080
	v_lshl_add_u64 v[194:195], v[196:197], 0, s[26:27]
	s_addc_u32 s63, s63, 0
	s_add_i32 s64, s97, s73
	global_load_lds_dwordx4 v[194:195], off
	v_lshl_add_u64 v[194:195], s[62:63], 0, v[202:203]
	s_mov_b32 m0, s64
	s_nop 0
	global_load_lds_dwordx4 v[194:195], off
	v_lshl_add_u64 v[194:195], s[62:63], 0, v[206:207]
	s_add_i32 m0, s64, 0x2000
	s_nop 0
	global_load_lds_dwordx4 v[194:195], off
	v_lshl_add_u64 v[194:195], v[220:221], 0, s[26:27]
	s_mov_b32 m0, s77
	s_nop 0
	global_load_lds_dwordx4 v[194:195], off
	v_lshl_add_u64 v[194:195], v[222:223], 0, s[26:27]
	s_mov_b32 m0, s78
	s_nop 0
	global_load_lds_dwordx4 v[194:195], off
	s_waitcnt vmcnt(8)
	s_waitcnt lgkmcnt(0)
	s_barrier
	s_setprio 1
	s_waitcnt lgkmcnt(0)
	v_mfma_f32_16x16x32_bf16 v[62:65], v[130:133], v[162:165], v[62:65]
	v_mfma_f32_16x16x32_bf16 v[58:61], v[138:141], v[162:165], v[58:61]
	v_mfma_f32_16x16x32_bf16 v[46:49], v[130:133], v[170:173], v[46:49]
	v_mfma_f32_16x16x32_bf16 v[42:45], v[138:141], v[170:173], v[42:45]
	v_mfma_f32_16x16x32_bf16 v[30:33], v[130:133], v[178:181], v[30:33]
	v_mfma_f32_16x16x32_bf16 v[26:29], v[138:141], v[178:181], v[26:29]
	v_mfma_f32_16x16x32_bf16 v[14:17], v[130:133], v[186:189], v[14:17]
	v_mfma_f32_16x16x32_bf16 v[10:13], v[138:141], v[186:189], v[10:13]
	v_mfma_f32_16x16x32_bf16 v[62:65], v[134:137], v[166:169], v[62:65]
	v_mfma_f32_16x16x32_bf16 v[58:61], v[142:145], v[166:169], v[58:61]
	v_mfma_f32_16x16x32_bf16 v[46:49], v[134:137], v[174:177], v[46:49]
	v_mfma_f32_16x16x32_bf16 v[42:45], v[142:145], v[174:177], v[42:45]
	v_mfma_f32_16x16x32_bf16 v[30:33], v[134:137], v[182:185], v[30:33]
	v_mfma_f32_16x16x32_bf16 v[26:29], v[142:145], v[182:185], v[26:29]
	v_mfma_f32_16x16x32_bf16 v[14:17], v[134:137], v[190:193], v[14:17]
	v_mfma_f32_16x16x32_bf16 v[10:13], v[142:145], v[190:193], v[10:13]
	v_mfma_f32_16x16x32_bf16 v[54:57], v[146:149], v[162:165], v[54:57]
	v_mfma_f32_16x16x32_bf16 v[50:53], v[154:157], v[162:165], v[50:53]
	v_mfma_f32_16x16x32_bf16 v[38:41], v[146:149], v[170:173], v[38:41]
	v_mfma_f32_16x16x32_bf16 v[34:37], v[154:157], v[170:173], v[34:37]
	v_mfma_f32_16x16x32_bf16 v[22:25], v[146:149], v[178:181], v[22:25]
	v_mfma_f32_16x16x32_bf16 v[18:21], v[154:157], v[178:181], v[18:21]
	v_mfma_f32_16x16x32_bf16 v[6:9], v[146:149], v[186:189], v[6:9]
	v_mfma_f32_16x16x32_bf16 v[2:5], v[154:157], v[186:189], v[2:5]
	v_mfma_f32_16x16x32_bf16 v[54:57], v[150:153], v[166:169], v[54:57]
	v_mfma_f32_16x16x32_bf16 v[50:53], v[158:161], v[166:169], v[50:53]
	v_mfma_f32_16x16x32_bf16 v[38:41], v[150:153], v[174:177], v[38:41]
	v_mfma_f32_16x16x32_bf16 v[34:37], v[158:161], v[174:177], v[34:37]
	v_mfma_f32_16x16x32_bf16 v[22:25], v[150:153], v[182:185], v[22:25]
	v_mfma_f32_16x16x32_bf16 v[18:21], v[158:161], v[182:185], v[18:21]
	v_mfma_f32_16x16x32_bf16 v[6:9], v[150:153], v[190:193], v[6:9]
	v_mfma_f32_16x16x32_bf16 v[2:5], v[158:161], v[190:193], v[2:5]
	s_setprio 0
	s_barrier
	s_add_i32 s95, s95, 2
	s_add_u32 s12, s12, 0x100
	s_addc_u32 s13, s13, 0
	s_add_u32 s93, s93, 0x100
	s_addc_u32 s94, s94, 0
	s_cmp_gt_u32 s95, 13
	s_cbranch_scc0 .LBB0_713
	s_and_b64 vcc, exec, s[28:29]
	s_cbranch_vccz .LBB0_716
	s_barrier

.LBB0_1200:
	ds_read_b128 v[120:123], v207
	ds_read_b128 v[132:135], v207 offset:1024
	ds_read_b128 v[136:139], v207 offset:2048
	ds_read_b128 v[140:143], v207 offset:3072
	ds_read_b128 v[144:147], v208
	ds_read_b128 v[148:151], v208 offset:1024
	ds_read_b128 v[152:155], v208 offset:2048
	ds_read_b128 v[156:159], v208 offset:3072
	s_add_u32 s34, s28, 0xfffc0080
	s_addc_u32 s35, s29, -1
	s_cmp_eq_u32 s61, 12
	s_cselect_b32 s41, s21, s35
	s_cselect_b32 s40, s57, s34
	s_cselect_b32 s35, s19, s60
	s_cselect_b32 s34, s58, s59
	v_lshl_add_u64 v[222:223], s[28:29], 0, v[190:191]
	s_add_i32 m0, s45, 0xc000
	ds_read_b128 v[160:163], v209
	ds_read_b128 v[164:167], v209 offset:1024
	ds_read_b128 v[168:171], v209 offset:2048
	ds_read_b128 v[172:175], v209 offset:3072
	ds_read_b128 v[176:179], v209 offset:4096
	ds_read_b128 v[210:213], v209 offset:5120
	ds_read_b128 v[214:217], v209 offset:6144
	ds_read_b128 v[218:221], v209 offset:7168
	global_load_lds_dwordx4 v[222:223], off
	v_lshl_add_u64 v[222:223], s[28:29], 0, v[192:193]
	s_add_i32 m0, s45, 0xe000
	s_nop 0
	global_load_lds_dwordx4 v[222:223], off
	s_waitcnt vmcnt(8)
	s_waitcnt lgkmcnt(0)
	s_barrier
	s_setprio 1
	s_waitcnt lgkmcnt(0)
	v_mfma_f32_16x16x32_bf16 v[128:131], v[120:123], v[160:163], v[128:131]
	v_mfma_f32_16x16x32_bf16 v[124:127], v[136:139], v[160:163], v[124:127]
	v_mfma_f32_16x16x32_bf16 v[108:111], v[120:123], v[168:171], v[108:111]
	v_mfma_f32_16x16x32_bf16 v[104:107], v[136:139], v[168:171], v[104:107]
	v_mfma_f32_16x16x32_bf16 v[92:95], v[120:123], v[176:179], v[92:95]
	v_mfma_f32_16x16x32_bf16 v[88:91], v[136:139], v[176:179], v[88:91]
	v_mfma_f32_16x16x32_bf16 v[76:79], v[120:123], v[214:217], v[76:79]
	v_mfma_f32_16x16x32_bf16 v[72:75], v[136:139], v[214:217], v[72:75]
	v_mfma_f32_16x16x32_bf16 v[128:131], v[132:135], v[164:167], v[128:131]
	v_mfma_f32_16x16x32_bf16 v[124:127], v[140:143], v[164:167], v[124:127]
	v_mfma_f32_16x16x32_bf16 v[108:111], v[132:135], v[172:175], v[108:111]
	v_mfma_f32_16x16x32_bf16 v[104:107], v[140:143], v[172:175], v[104:107]
	v_mfma_f32_16x16x32_bf16 v[92:95], v[132:135], v[210:213], v[92:95]
	v_mfma_f32_16x16x32_bf16 v[88:91], v[140:143], v[210:213], v[88:91]
	v_mfma_f32_16x16x32_bf16 v[76:79], v[132:135], v[218:221], v[76:79]
	v_mfma_f32_16x16x32_bf16 v[72:75], v[140:143], v[218:221], v[72:75]
	v_mfma_f32_16x16x32_bf16 v[116:119], v[144:147], v[160:163], v[116:119]
	v_mfma_f32_16x16x32_bf16 v[112:115], v[152:155], v[160:163], v[112:115]
	v_mfma_f32_16x16x32_bf16 v[100:103], v[144:147], v[168:171], v[100:103]
	v_mfma_f32_16x16x32_bf16 v[96:99], v[152:155], v[168:171], v[96:99]
	v_mfma_f32_16x16x32_bf16 v[84:87], v[144:147], v[176:179], v[84:87]
	v_mfma_f32_16x16x32_bf16 v[80:83], v[152:155], v[176:179], v[80:83]
	v_mfma_f32_16x16x32_bf16 v[68:71], v[144:147], v[214:217], v[68:71]
	v_mfma_f32_16x16x32_bf16 v[64:67], v[152:155], v[214:217], v[64:67]
	v_mfma_f32_16x16x32_bf16 v[116:119], v[148:151], v[164:167], v[116:119]
	v_mfma_f32_16x16x32_bf16 v[112:115], v[156:159], v[164:167], v[112:115]
	v_mfma_f32_16x16x32_bf16 v[100:103], v[148:151], v[172:175], v[100:103]
	v_mfma_f32_16x16x32_bf16 v[96:99], v[156:159], v[172:175], v[96:99]
	v_mfma_f32_16x16x32_bf16 v[84:87], v[148:151], v[210:213], v[84:87]
	v_mfma_f32_16x16x32_bf16 v[80:83], v[156:159], v[210:213], v[80:83]
	v_mfma_f32_16x16x32_bf16 v[68:71], v[148:151], v[218:221], v[68:71]
	v_mfma_f32_16x16x32_bf16 v[64:67], v[156:159], v[218:221], v[64:67]
	s_setprio 0
	s_barrier
	s_add_i32 s62, s53, s44
	v_lshl_add_u64 v[222:223], s[34:35], 0, v[182:183]
	s_mov_b32 m0, s62
	ds_read_b128 v[160:163], v209 offset:16384
	ds_read_b128 v[164:167], v209 offset:17408
	ds_read_b128 v[168:171], v209 offset:18432
	ds_read_b128 v[172:175], v209 offset:19456
	ds_read_b128 v[176:179], v209 offset:20480
	ds_read_b128 v[210:213], v209 offset:21504
	ds_read_b128 v[214:217], v209 offset:22528
	ds_read_b128 v[218:221], v209 offset:23552
	global_load_lds_dwordx4 v[222:223], off
	s_add_i32 m0, s62, 0x2000
	s_add_u32 s62, s34, 0x40000
	v_lshl_add_u64 v[224:225], s[34:35], 0, v[186:187]
	s_addc_u32 s63, s35, 0
	s_add_i32 s64, s54, s44
	global_load_lds_dwordx4 v[224:225], off
	v_lshl_add_u64 v[226:227], s[62:63], 0, v[182:183]
	s_mov_b32 m0, s64
	v_lshl_add_u64 v[228:229], s[40:41], 0, v[184:185]
	global_load_lds_dwordx4 v[226:227], off
	v_lshl_add_u64 v[226:227], s[62:63], 0, v[186:187]
	s_add_i32 m0, s64, 0x2000
	s_nop 0
	global_load_lds_dwordx4 v[226:227], off
	v_lshl_add_u64 v[226:227], s[40:41], 0, v[180:181]
	s_mov_b32 m0, s45
	s_nop 0
	global_load_lds_dwordx4 v[226:227], off
	s_mov_b32 m0, s46
	s_nop 0
	global_load_lds_dwordx4 v[228:229], off
	s_waitcnt vmcnt(8)
	s_waitcnt lgkmcnt(0)
	s_barrier
	s_setprio 1
	s_waitcnt lgkmcnt(0)
	v_mfma_f32_16x16x32_bf16 v[60:63], v[120:123], v[160:163], v[60:63]
	v_mfma_f32_16x16x32_bf16 v[56:59], v[136:139], v[160:163], v[56:59]
	v_mfma_f32_16x16x32_bf16 v[44:47], v[120:123], v[168:171], v[44:47]
	v_mfma_f32_16x16x32_bf16 v[40:43], v[136:139], v[168:171], v[40:43]
	v_mfma_f32_16x16x32_bf16 v[28:31], v[120:123], v[176:179], v[28:31]
	v_mfma_f32_16x16x32_bf16 v[24:27], v[136:139], v[176:179], v[24:27]
	v_mfma_f32_16x16x32_bf16 v[12:15], v[120:123], v[214:217], v[12:15]
	v_mfma_f32_16x16x32_bf16 v[8:11], v[136:139], v[214:217], v[8:11]
	v_mfma_f32_16x16x32_bf16 v[60:63], v[132:135], v[164:167], v[60:63]
	v_mfma_f32_16x16x32_bf16 v[56:59], v[140:143], v[164:167], v[56:59]
	v_mfma_f32_16x16x32_bf16 v[44:47], v[132:135], v[172:175], v[44:47]
	v_mfma_f32_16x16x32_bf16 v[40:43], v[140:143], v[172:175], v[40:43]
	v_mfma_f32_16x16x32_bf16 v[28:31], v[132:135], v[210:213], v[28:31]
	v_mfma_f32_16x16x32_bf16 v[24:27], v[140:143], v[210:213], v[24:27]
	v_mfma_f32_16x16x32_bf16 v[12:15], v[132:135], v[218:221], v[12:15]
	v_mfma_f32_16x16x32_bf16 v[8:11], v[140:143], v[218:221], v[8:11]
	v_mfma_f32_16x16x32_bf16 v[52:55], v[144:147], v[160:163], v[52:55]
	v_mfma_f32_16x16x32_bf16 v[48:51], v[152:155], v[160:163], v[48:51]
	v_mfma_f32_16x16x32_bf16 v[36:39], v[144:147], v[168:171], v[36:39]
	v_mfma_f32_16x16x32_bf16 v[32:35], v[152:155], v[168:171], v[32:35]
	v_mfma_f32_16x16x32_bf16 v[20:23], v[144:147], v[176:179], v[20:23]
	v_mfma_f32_16x16x32_bf16 v[16:19], v[152:155], v[176:179], v[16:19]
	v_mfma_f32_16x16x32_bf16 v[4:7], v[144:147], v[214:217], v[4:7]
	v_mfma_f32_16x16x32_bf16 v[0:3], v[152:155], v[214:217], v[0:3]
	v_mfma_f32_16x16x32_bf16 v[52:55], v[148:151], v[164:167], v[52:55]
	v_mfma_f32_16x16x32_bf16 v[48:51], v[156:159], v[164:167], v[48:51]
	v_mfma_f32_16x16x32_bf16 v[36:39], v[148:151], v[172:175], v[36:39]
	v_mfma_f32_16x16x32_bf16 v[32:35], v[156:159], v[172:175], v[32:35]
	v_mfma_f32_16x16x32_bf16 v[20:23], v[148:151], v[210:213], v[20:23]
	v_mfma_f32_16x16x32_bf16 v[16:19], v[156:159], v[210:213], v[16:19]
	v_mfma_f32_16x16x32_bf16 v[4:7], v[148:151], v[218:221], v[4:7]
	v_mfma_f32_16x16x32_bf16 v[0:3], v[156:159], v[218:221], v[0:3]
	s_setprio 0
	s_barrier
	s_add_i32 s62, 0, 0x18000
	s_add_i32 s63, 0, 0x1c000
	v_add_u32_e32 v140, s62, v201
	v_add_u32_e32 v156, s63, v201
	ds_read_b128 v[120:123], v140
	ds_read_b128 v[132:135], v140 offset:1024
	ds_read_b128 v[136:139], v140 offset:2048
	ds_read_b128 v[140:143], v140 offset:3072
	ds_read_b128 v[144:147], v156
	ds_read_b128 v[148:151], v156 offset:1024
	ds_read_b128 v[152:155], v156 offset:2048
	ds_read_b128 v[156:159], v156 offset:3072
	s_add_u32 s40, s40, 0x40000
	s_addc_u32 s41, s41, 0
	s_mov_b32 m0, s47
	v_lshl_add_u64 v[230:231], s[40:41], 0, v[180:181]
	ds_read_b128 v[160:163], v209 offset:32768
	ds_read_b128 v[164:167], v209 offset:33792
	ds_read_b128 v[168:171], v209 offset:34816
	ds_read_b128 v[172:175], v209 offset:35840
	ds_read_b128 v[176:179], v209 offset:36864
	ds_read_b128 v[210:213], v209 offset:37888
	ds_read_b128 v[214:217], v209 offset:38912
	ds_read_b128 v[218:221], v209 offset:39936
	global_load_lds_dwordx4 v[230:231], off
	v_lshl_add_u64 v[230:231], s[40:41], 0, v[184:185]
	s_mov_b32 m0, s48
	s_nop 0
	global_load_lds_dwordx4 v[230:231], off
	s_waitcnt vmcnt(8)
	s_waitcnt lgkmcnt(0)
	s_barrier
	s_setprio 1
	s_waitcnt lgkmcnt(0)
	v_mfma_f32_16x16x32_bf16 v[128:131], v[120:123], v[160:163], v[128:131]
	v_mfma_f32_16x16x32_bf16 v[124:127], v[136:139], v[160:163], v[124:127]
	v_mfma_f32_16x16x32_bf16 v[108:111], v[120:123], v[168:171], v[108:111]
	v_mfma_f32_16x16x32_bf16 v[104:107], v[136:139], v[168:171], v[104:107]
	v_mfma_f32_16x16x32_bf16 v[92:95], v[120:123], v[176:179], v[92:95]
	v_mfma_f32_16x16x32_bf16 v[88:91], v[136:139], v[176:179], v[88:91]
	v_mfma_f32_16x16x32_bf16 v[76:79], v[120:123], v[214:217], v[76:79]
	v_mfma_f32_16x16x32_bf16 v[72:75], v[136:139], v[214:217], v[72:75]
	v_mfma_f32_16x16x32_bf16 v[128:131], v[132:135], v[164:167], v[128:131]
	v_mfma_f32_16x16x32_bf16 v[124:127], v[140:143], v[164:167], v[124:127]
	v_mfma_f32_16x16x32_bf16 v[108:111], v[132:135], v[172:175], v[108:111]
	v_mfma_f32_16x16x32_bf16 v[104:107], v[140:143], v[172:175], v[104:107]
	v_mfma_f32_16x16x32_bf16 v[92:95], v[132:135], v[210:213], v[92:95]
	v_mfma_f32_16x16x32_bf16 v[88:91], v[140:143], v[210:213], v[88:91]
	v_mfma_f32_16x16x32_bf16 v[76:79], v[132:135], v[218:221], v[76:79]
	v_mfma_f32_16x16x32_bf16 v[72:75], v[140:143], v[218:221], v[72:75]
	v_mfma_f32_16x16x32_bf16 v[116:119], v[144:147], v[160:163], v[116:119]
	v_mfma_f32_16x16x32_bf16 v[112:115], v[152:155], v[160:163], v[112:115]
	v_mfma_f32_16x16x32_bf16 v[100:103], v[144:147], v[168:171], v[100:103]
	v_mfma_f32_16x16x32_bf16 v[96:99], v[152:155], v[168:171], v[96:99]
	v_mfma_f32_16x16x32_bf16 v[84:87], v[144:147], v[176:179], v[84:87]
	v_mfma_f32_16x16x32_bf16 v[80:83], v[152:155], v[176:179], v[80:83]
	v_mfma_f32_16x16x32_bf16 v[68:71], v[144:147], v[214:217], v[68:71]
	v_mfma_f32_16x16x32_bf16 v[64:67], v[152:155], v[214:217], v[64:67]
	v_mfma_f32_16x16x32_bf16 v[116:119], v[148:151], v[164:167], v[116:119]
	v_mfma_f32_16x16x32_bf16 v[112:115], v[156:159], v[164:167], v[112:115]
	v_mfma_f32_16x16x32_bf16 v[100:103], v[148:151], v[172:175], v[100:103]
	v_mfma_f32_16x16x32_bf16 v[96:99], v[156:159], v[172:175], v[96:99]
	v_mfma_f32_16x16x32_bf16 v[84:87], v[148:151], v[210:213], v[84:87]
	v_mfma_f32_16x16x32_bf16 v[80:83], v[156:159], v[210:213], v[80:83]
	v_mfma_f32_16x16x32_bf16 v[68:71], v[148:151], v[218:221], v[68:71]
	v_mfma_f32_16x16x32_bf16 v[64:67], v[156:159], v[218:221], v[64:67]
	s_setprio 0
	s_barrier
	s_add_i32 s40, s62, s44
	v_lshl_add_u64 v[222:223], v[222:223], 0, s[12:13]
	s_mov_b32 m0, s40
	ds_read_b128 v[160:163], v209 offset:49152
	ds_read_b128 v[164:167], v209 offset:50176
	ds_read_b128 v[168:171], v209 offset:51200
	ds_read_b128 v[172:175], v209 offset:52224
	ds_read_b128 v[176:179], v209 offset:53248
	ds_read_b128 v[210:213], v209 offset:54272
	ds_read_b128 v[214:217], v209 offset:55296
	ds_read_b128 v[218:221], v209 offset:56320
	global_load_lds_dwordx4 v[222:223], off
	s_add_i32 m0, s40, 0x2000
	s_add_u32 s34, s34, 0x40080
	v_lshl_add_u64 v[222:223], v[224:225], 0, s[12:13]
	s_addc_u32 s35, s35, 0
	s_add_i32 s40, s63, s44
	global_load_lds_dwordx4 v[222:223], off
	v_lshl_add_u64 v[222:223], s[34:35], 0, v[182:183]
	s_mov_b32 m0, s40
	s_nop 0
	global_load_lds_dwordx4 v[222:223], off
	v_lshl_add_u64 v[222:223], s[34:35], 0, v[186:187]
	s_add_i32 m0, s40, 0x2000
	s_nop 0
	global_load_lds_dwordx4 v[222:223], off
	v_lshl_add_u64 v[222:223], v[226:227], 0, s[12:13]
	s_mov_b32 m0, s49
	s_nop 0
	global_load_lds_dwordx4 v[222:223], off
	v_lshl_add_u64 v[222:223], v[228:229], 0, s[12:13]
	s_mov_b32 m0, s50
	s_nop 0
	global_load_lds_dwordx4 v[222:223], off
	s_waitcnt vmcnt(8)
	s_waitcnt lgkmcnt(0)
	s_barrier
	s_setprio 1
	s_waitcnt lgkmcnt(0)
	v_mfma_f32_16x16x32_bf16 v[60:63], v[120:123], v[160:163], v[60:63]
	v_mfma_f32_16x16x32_bf16 v[56:59], v[136:139], v[160:163], v[56:59]
	v_mfma_f32_16x16x32_bf16 v[44:47], v[120:123], v[168:171], v[44:47]
	v_mfma_f32_16x16x32_bf16 v[40:43], v[136:139], v[168:171], v[40:43]
	v_mfma_f32_16x16x32_bf16 v[28:31], v[120:123], v[176:179], v[28:31]
	v_mfma_f32_16x16x32_bf16 v[24:27], v[136:139], v[176:179], v[24:27]
	v_mfma_f32_16x16x32_bf16 v[12:15], v[120:123], v[214:217], v[12:15]
	v_mfma_f32_16x16x32_bf16 v[8:11], v[136:139], v[214:217], v[8:11]
	v_mfma_f32_16x16x32_bf16 v[60:63], v[132:135], v[164:167], v[60:63]
	v_mfma_f32_16x16x32_bf16 v[56:59], v[140:143], v[164:167], v[56:59]
	v_mfma_f32_16x16x32_bf16 v[44:47], v[132:135], v[172:175], v[44:47]
	v_mfma_f32_16x16x32_bf16 v[40:43], v[140:143], v[172:175], v[40:43]
	v_mfma_f32_16x16x32_bf16 v[28:31], v[132:135], v[210:213], v[28:31]
	v_mfma_f32_16x16x32_bf16 v[24:27], v[140:143], v[210:213], v[24:27]
	v_mfma_f32_16x16x32_bf16 v[12:15], v[132:135], v[218:221], v[12:15]
	v_mfma_f32_16x16x32_bf16 v[8:11], v[140:143], v[218:221], v[8:11]
	v_mfma_f32_16x16x32_bf16 v[52:55], v[144:147], v[160:163], v[52:55]
	v_mfma_f32_16x16x32_bf16 v[48:51], v[152:155], v[160:163], v[48:51]
	v_mfma_f32_16x16x32_bf16 v[36:39], v[144:147], v[168:171], v[36:39]
	v_mfma_f32_16x16x32_bf16 v[32:35], v[152:155], v[168:171], v[32:35]
	v_mfma_f32_16x16x32_bf16 v[20:23], v[144:147], v[176:179], v[20:23]
	v_mfma_f32_16x16x32_bf16 v[16:19], v[152:155], v[176:179], v[16:19]
	v_mfma_f32_16x16x32_bf16 v[4:7], v[144:147], v[214:217], v[4:7]
	v_mfma_f32_16x16x32_bf16 v[0:3], v[152:155], v[214:217], v[0:3]
	v_mfma_f32_16x16x32_bf16 v[52:55], v[148:151], v[164:167], v[52:55]
	v_mfma_f32_16x16x32_bf16 v[48:51], v[156:159], v[164:167], v[48:51]
	v_mfma_f32_16x16x32_bf16 v[36:39], v[148:151], v[172:175], v[36:39]
	v_mfma_f32_16x16x32_bf16 v[32:35], v[156:159], v[172:175], v[32:35]
	v_mfma_f32_16x16x32_bf16 v[20:23], v[148:151], v[210:213], v[20:23]
	v_mfma_f32_16x16x32_bf16 v[16:19], v[156:159], v[210:213], v[16:19]
	v_mfma_f32_16x16x32_bf16 v[4:7], v[148:151], v[218:221], v[4:7]
	v_mfma_f32_16x16x32_bf16 v[0:3], v[156:159], v[218:221], v[0:3]
	s_setprio 0
	s_barrier
	s_add_i32 s61, s61, 2
	s_add_u32 s28, s28, 0x100
	s_addc_u32 s29, s29, 0
	s_add_u32 s59, s59, 0x100
	s_addc_u32 s60, s60, 0
	s_cmp_gt_u32 s61, 13
	s_cbranch_scc0 .LBB0_1200
	s_and_b64 vcc, exec, s[14:15]
	s_cbranch_vccz .LBB0_1203
	s_barrier
